# instruction selection in NA softmax: scale/shift as v_pk_fma_f32 (same fused rounding) and row sum via v_pk_add_f32 (31+32 VALU -> 17+18 per tile)
# baseline (speedup 1.0000x reference)
; #define NA_SBAR() __builtin_amdgcn_sched_barrier(0)
; __device__ __forceinline__ void partialSM(f32x16& p0, f32x16& p1, float& m_reg, float& mn, float& alpha) {
;     ...
;   else { mn = fmaxf(m_reg, pmax); alpha = __builtin_amdgcn_exp2f((m_reg - mn) * C); m_reg = mn; }
;   float mnC = -mn * C;
; #pragma unroll
;   for (int r = 0; r < 16; ++r) p0[r] = fmaf(p0[r], C, mnC);
; #pragma unroll
;   for (int r = 0; r < 16; ++r) p1[r] = fmaf(p1[r], C, mnC);
; #pragma unroll
;   for (int r = 0; r < 16; ++r) p0[r] = __builtin_amdgcn_exp2f(p0[r]);
; }
; __device__ __forceinline__ void finishSM(f32x16& p0, f32x16& p1, float alpha, float& l_reg, bf16x8& pa0, bf16x8& pa1, bf16x8& pa2, bf16x8& pa3) {
; #pragma unroll
;   for (int r = 0; r < 16; ++r) p1[r] = __builtin_amdgcn_exp2f(p1[r]);
;   float ps = 0;
; #pragma unroll
;   for (int r = 0; r < 16; ++r) ps += p0[r];
; #pragma unroll
;   for (int r = 0; r < 16; ++r) ps += p1[r];
;   { auto rr = __builtin_amdgcn_permlane32_swap(__float_as_uint(ps), __float_as_uint(ps), false, false);
;     ps = __uint_as_float(rr[0]) + __uint_as_float(rr[1]); }
;   l_reg = l_reg * alpha + ps;
;     ...
;   NA_PK4(p0, 0, pa0); NA_PK4(p0, 8, pa1); NA_PK4(p1, 0, pa2); NA_PK4(p1, 8, pa3);
; template <int D0> __device__ __forceinline__ void pv_one(f32x16& od, int vb, bf16x8 pa0, bf16x8 pa1, bf16x8 pa2, bf16x8 pa3) {
;   const s16x4 l0 = tr_read<v_rd_off(D0, 0, 0)>(vb), h0 = tr_read<v_rd_off(D0, 0, 1)>(vb), l1 = tr_read<v_rd_off(D0, 1, 0)>(vb), h1 = tr_read<v_rd_off(D0, 1, 1)>(vb);
;   const s16x4 l2 = tr_read<v_rd_off(D0, 2, 0)>(vb), h2 = tr_read<v_rd_off(D0, 2, 1)>(vb), l3 = tr_read<v_rd_off(D0, 3, 0)>(vb), h3 = tr_read<v_rd_off(D0, 3, 1)>(vb);
;   asm volatile("s_waitcnt lgkmcnt(0)" ::: "memory"); NA_SBAR();
;     ...
;   od = __builtin_amdgcn_mfma_f32_32x32x16_bf16(pa0, NA_PK(l0, h0), od, 0, 0, 0);
;   od = __builtin_amdgcn_mfma_f32_32x32x16_bf16(pa1, NA_PK(l1, h1), od, 0, 0, 0);
;   od = __builtin_amdgcn_mfma_f32_32x32x16_bf16(pa2, NA_PK(l2, h2), od, 0, 0, 0);
;   od = __builtin_amdgcn_mfma_f32_32x32x16_bf16(pa3, NA_PK(l3, h3), od, 0, 0, 0);
;     ...
; }
; __device__ __forceinline__ void pv_d0(f32x16* o, int vb, bf16x8 pa0, bf16x8 pa1, bf16x8 pa2, bf16x8 pa3) {
;   pv_one<0>(o[0], vb, pa0, pa1, pa2, pa3); pv_one<1>(o[1], vb, pa0, pa1, pa2, pa3); pv_one<2>(o[2], vb, pa0, pa1, pa2, pa3); pv_one<3>(o[3], vb, pa0, pa1, pa2, pa3);
.LBB0_709:
	v_cndmask_b32_e64 v129, v164, v129, s[4:5]
	v_mul_f32_e32 v164, 0xbe0293ee, v129
	s_mov_b32 s32, 0x3e0293ee
	v_pk_fma_f32 v[84:85], v[84:85], s[32:33], v[164:165] op_sel_hi:[1,0,0]
	v_pk_fma_f32 v[86:87], v[86:87], s[32:33], v[164:165] op_sel_hi:[1,0,0]
	v_pk_fma_f32 v[88:89], v[88:89], s[32:33], v[164:165] op_sel_hi:[1,0,0]
	v_pk_fma_f32 v[90:91], v[90:91], s[32:33], v[164:165] op_sel_hi:[1,0,0]
	v_pk_fma_f32 v[92:93], v[92:93], s[32:33], v[164:165] op_sel_hi:[1,0,0]
	v_pk_fma_f32 v[94:95], v[94:95], s[32:33], v[164:165] op_sel_hi:[1,0,0]
	v_pk_fma_f32 v[96:97], v[96:97], s[32:33], v[164:165] op_sel_hi:[1,0,0]
	v_pk_fma_f32 v[98:99], v[98:99], s[32:33], v[164:165] op_sel_hi:[1,0,0]
	v_pk_fma_f32 v[68:69], v[68:69], s[32:33], v[164:165] op_sel_hi:[1,0,0]
	v_pk_fma_f32 v[70:71], v[70:71], s[32:33], v[164:165] op_sel_hi:[1,0,0]
	v_pk_fma_f32 v[72:73], v[72:73], s[32:33], v[164:165] op_sel_hi:[1,0,0]
	v_pk_fma_f32 v[74:75], v[74:75], s[32:33], v[164:165] op_sel_hi:[1,0,0]
	v_pk_fma_f32 v[76:77], v[76:77], s[32:33], v[164:165] op_sel_hi:[1,0,0]
	v_pk_fma_f32 v[78:79], v[78:79], s[32:33], v[164:165] op_sel_hi:[1,0,0]
	v_pk_fma_f32 v[80:81], v[80:81], s[32:33], v[164:165] op_sel_hi:[1,0,0]
	v_fmamk_f32 v82, v82, 0x3e0293ee, v164
	v_fmac_f32_e32 v164, 0x3e0293ee, v83
	v_exp_f32_e32 v83, v84
	v_exp_f32_e32 v84, v85
	v_exp_f32_e32 v85, v86
	v_exp_f32_e32 v86, v87
	v_exp_f32_e32 v87, v88
	v_exp_f32_e32 v88, v89
	v_exp_f32_e32 v89, v90
	v_exp_f32_e32 v90, v91
	v_exp_f32_e32 v91, v92
	v_exp_f32_e32 v92, v93
	v_exp_f32_e32 v93, v94
	v_exp_f32_e32 v94, v95
	v_exp_f32_e32 v95, v96
	v_exp_f32_e32 v96, v97
	v_exp_f32_e32 v97, v98
	v_exp_f32_e32 v98, v99
	v_exp_f32_e32 v99, v68
	v_exp_f32_e32 v165, v69
	v_exp_f32_e32 v166, v70
	v_exp_f32_e32 v167, v71
	v_exp_f32_e32 v168, v72
	v_exp_f32_e32 v169, v73
	v_exp_f32_e32 v170, v74
	v_exp_f32_e32 v171, v75
	v_exp_f32_e32 v172, v76
	v_exp_f32_e32 v173, v77
	v_exp_f32_e32 v174, v78
	v_exp_f32_e32 v175, v79
	v_exp_f32_e32 v176, v80
	v_exp_f32_e32 v177, v81
	v_exp_f32_e32 v178, v82
	v_exp_f32_e32 v164, v164
	s_nop 0
	v_pk_add_f32 v[68:69], v[84:85], v[86:87]
	v_pk_add_f32 v[68:69], v[68:69], v[88:89]
	v_pk_add_f32 v[68:69], v[68:69], v[90:91]
	v_pk_add_f32 v[68:69], v[68:69], v[92:93]
	v_pk_add_f32 v[68:69], v[68:69], v[94:95]
	v_pk_add_f32 v[68:69], v[68:69], v[96:97]
	v_pk_add_f32 v[68:69], v[68:69], v[98:99]
	v_pk_add_f32 v[68:69], v[68:69], v[166:167]
	v_pk_add_f32 v[68:69], v[68:69], v[168:169]
	v_pk_add_f32 v[68:69], v[68:69], v[170:171]
	v_pk_add_f32 v[68:69], v[68:69], v[172:173]
	v_pk_add_f32 v[68:69], v[68:69], v[174:175]
	v_pk_add_f32 v[68:69], v[68:69], v[176:177]
	v_add_f32_e32 v68, v68, v69
	v_add_f32_e32 v68, v83, v68
	v_add_f32_e32 v68, v165, v68
	v_add_f32_e32 v68, v178, v68
	v_add_f32_e32 v68, v164, v68
	v_mov_b32_e32 v69, v68
	s_nop 1
	v_permlane32_swap_b32_e32 v68, v69
	v_add_f32_e32 v179, v68, v69
	v_cvt_pk_bf16_f32 v68, v83, v84
	v_cvt_pk_bf16_f32 v69, v85, v86
	v_cvt_pk_bf16_f32 v70, v87, v88
	v_cvt_pk_bf16_f32 v71, v89, v90
	v_cvt_pk_bf16_f32 v72, v91, v92
	v_cvt_pk_bf16_f32 v73, v93, v94
	v_cvt_pk_bf16_f32 v74, v95, v96
	v_cvt_pk_bf16_f32 v75, v97, v98
	v_cvt_pk_bf16_f32 v76, v99, v165
	v_cvt_pk_bf16_f32 v77, v166, v167
	v_cvt_pk_bf16_f32 v78, v168, v169
	v_cvt_pk_bf16_f32 v79, v170, v171
	v_cvt_pk_bf16_f32 v80, v172, v173
	v_cvt_pk_bf16_f32 v81, v174, v175
	v_cvt_pk_bf16_f32 v82, v176, v177
	v_cvt_pk_bf16_f32 v83, v178, v164
	v_fmac_f32_e32 v179, v158, v163
	v_permlane32_swap_b32_e32 v68, v70
	v_permlane32_swap_b32_e32 v69, v71
	v_permlane32_swap_b32_e32 v72, v74
	v_permlane32_swap_b32_e32 v73, v75
	v_permlane32_swap_b32_e32 v76, v78
	v_permlane32_swap_b32_e32 v77, v79
	v_permlane32_swap_b32_e32 v80, v82
	v_permlane32_swap_b32_e32 v81, v83
	v_add_u32_e32 v158, s59, v151
	ds_read_b64_tr_b16 v[84:85], v158 offset:0
	ds_read_b64_tr_b16 v[86:87], v158 offset:0x800
	ds_read_b64_tr_b16 v[88:89], v158 offset:0x1000
	ds_read_b64_tr_b16 v[90:91], v158 offset:0x1800
	ds_read_b64_tr_b16 v[92:93], v158 offset:0x2000
	ds_read_b64_tr_b16 v[94:95], v158 offset:0x2800
	ds_read_b64_tr_b16 v[96:97], v158 offset:0x3000
	ds_read_b64_tr_b16 v[98:99], v158 offset:0x3800
	s_waitcnt lgkmcnt(0)
	s_nop 0
	v_mfma_f32_32x32x16_bf16 v[4:19], v[68:71], v[84:87], v[4:19]
	ds_read_b64_tr_b16 v[84:85], v158 offset:0x200
	ds_read_b64_tr_b16 v[86:87], v158 offset:0xa00
	v_mfma_f32_32x32x16_bf16 v[4:19], v[72:75], v[88:91], v[4:19]
	ds_read_b64_tr_b16 v[88:89], v158 offset:0x1200
	ds_read_b64_tr_b16 v[90:91], v158 offset:0x1a00
	v_mfma_f32_32x32x16_bf16 v[4:19], v[76:79], v[92:95], v[4:19]
	ds_read_b64_tr_b16 v[92:93], v158 offset:0x2200
	ds_read_b64_tr_b16 v[94:95], v158 offset:0x2a00
	v_mfma_f32_32x32x16_bf16 v[4:19], v[80:83], v[96:99], v[4:19]
	ds_read_b64_tr_b16 v[96:97], v158 offset:0x3200
	ds_read_b64_tr_b16 v[98:99], v158 offset:0x3a00
	s_waitcnt lgkmcnt(0)
	v_mfma_f32_32x32x16_bf16 v[52:67], v[68:71], v[84:87], v[52:67]
	ds_read_b64_tr_b16 v[84:85], v158 offset:0x400
	ds_read_b64_tr_b16 v[86:87], v158 offset:0xc00
	v_mfma_f32_32x32x16_bf16 v[52:67], v[72:75], v[88:91], v[52:67]
	ds_read_b64_tr_b16 v[88:89], v158 offset:0x1400
	ds_read_b64_tr_b16 v[90:91], v158 offset:0x1c00
	v_mfma_f32_32x32x16_bf16 v[52:67], v[76:79], v[92:95], v[52:67]
	ds_read_b64_tr_b16 v[92:93], v158 offset:0x2400
	ds_read_b64_tr_b16 v[94:95], v158 offset:0x2c00
	v_mfma_f32_32x32x16_bf16 v[52:67], v[80:83], v[96:99], v[52:67]
	ds_read_b64_tr_b16 v[96:97], v158 offset:0x3400
	ds_read_b64_tr_b16 v[98:99], v158 offset:0x3c00
	s_waitcnt lgkmcnt(0)
	v_mfma_f32_32x32x16_bf16 v[36:51], v[68:71], v[84:87], v[36:51]
	ds_read_b64_tr_b16 v[84:85], v158 offset:0x600
	ds_read_b64_tr_b16 v[86:87], v158 offset:0xe00
	v_mfma_f32_32x32x16_bf16 v[36:51], v[72:75], v[88:91], v[36:51]
	ds_read_b64_tr_b16 v[88:89], v158 offset:0x1600
	ds_read_b64_tr_b16 v[90:91], v158 offset:0x1e00
	v_mfma_f32_32x32x16_bf16 v[36:51], v[76:79], v[92:95], v[36:51]
	ds_read_b64_tr_b16 v[92:93], v158 offset:0x2600
	ds_read_b64_tr_b16 v[94:95], v158 offset:0x2e00
	v_mfma_f32_32x32x16_bf16 v[36:51], v[80:83], v[96:99], v[36:51]
	ds_read_b64_tr_b16 v[96:97], v158 offset:0x3600
	ds_read_b64_tr_b16 v[98:99], v158 offset:0x3e00
	s_waitcnt lgkmcnt(0)
	v_mfma_f32_32x32x16_bf16 v[20:35], v[68:71], v[84:87], v[20:35]
	v_mov_b32_e32 v158, v179
	v_mfma_f32_32x32x16_bf16 v[20:35], v[72:75], v[88:91], v[20:35]
	v_mfma_f32_32x32x16_bf16 v[20:35], v[76:79], v[92:95], v[20:35]
	v_mfma_f32_32x32x16_bf16 v[20:35], v[80:83], v[96:99], v[20:35]
